# layer-0 projection rotary epilogues: removed the two redundant vmcnt(0) re-waits per row group (table pair already waited at first use; they only drained stores)
# speedup vs baseline: 1.0407x; 1.0407x over previous
.LBB0_328:
	s_or_b64 exec, exec, s[10:11]
	s_and_b64 vcc, exec, s[4:5]
	v_mov_b32_e32 v140, v112
	v_mov_b32_e32 v141, v113
	v_mov_b32_e32 v142, v114
	v_mov_b32_e32 v143, v115
	v_mov_b32_e32 v136, v116
	v_mov_b32_e32 v137, v117
	v_mov_b32_e32 v138, v118
	v_mov_b32_e32 v139, v119
	s_cbranch_vccnz .LBB0_330
	v_pk_mul_f32 v[192:193], v[116:117], v[132:133] op_sel:[1,0] op_sel_hi:[0,0]
	v_pk_mul_f32 v[146:147], v[116:117], v[128:129]
	v_pk_fma_f32 v[136:137], v[116:117], v[128:129], v[192:193] op_sel_hi:[1,0,1]
	v_mov_b32_e32 v132, v129
	v_mul_f32_e32 v128, v119, v133
	v_pk_fma_f32 v[138:139], v[118:119], v[132:133], v[128:129] op_sel_hi:[1,1,0] neg_lo:[0,0,1] neg_hi:[0,0,1]
	v_mov_b32_e32 v128, v133
	v_mul_f32_e32 v132, v119, v129
	v_pk_mul_f32 v[194:195], v[112:113], v[134:135] op_sel:[1,0] op_sel_hi:[0,0]
	v_pk_fma_f32 v[128:129], v[118:119], v[128:129], v[132:133] op_sel_hi:[1,1,0]
	v_pk_mul_f32 v[132:133], v[112:113], v[130:131]
	v_pk_fma_f32 v[140:141], v[112:113], v[130:131], v[194:195] op_sel_hi:[1,0,1]
	v_mov_b32_e32 v134, v131
	v_mul_f32_e32 v130, v115, v135
	v_pk_fma_f32 v[142:143], v[114:115], v[134:135], v[130:131] op_sel_hi:[1,1,0] neg_lo:[0,0,1] neg_hi:[0,0,1]
	v_mov_b32_e32 v130, v135
	v_mul_f32_e32 v134, v115, v131
	v_pk_fma_f32 v[130:131], v[114:115], v[130:131], v[134:135] op_sel_hi:[1,1,0]
	v_sub_f32_e32 v140, v132, v194
	v_sub_f32_e32 v136, v146, v192
	v_mov_b32_e32 v143, v130
	v_mov_b32_e32 v139, v128
.LBB0_330:
	v_cvt_pk_bf16_f32 v128, v136, v137
	v_cvt_pk_bf16_f32 v129, v138, v139
	v_cvt_pk_bf16_f32 v130, v140, v141
	v_cvt_pk_bf16_f32 v131, v142, v143
	global_store_dwordx4 v[174:175], v[128:131], off offset:256
	s_and_saveexec_b64 s[10:11], s[6:7]
	s_cbranch_execz .LBB0_332
	s_lshl_b32 s6, s82, 21
	s_add_i32 s6, s6, 0xfc900000
	v_lshlrev_b32_e32 v132, 3, v184
	v_add_u32_e32 v134, s6, v186
	v_and_b32_e32 v132, 0xf8, v132
	s_movk_i32 s6, 0xf000
	v_and_or_b32 v132, v191, s6, v132
	v_add_u32_e32 v156, v132, v134
	v_lshl_add_u64 v[132:133], v[156:157], 1, s[88:89]
	global_store_dwordx4 v[132:133], v[128:131], off
	v_add_u32_e32 v132, v177, v188
	v_lshl_or_b32 v132, v132, 12, v190
	s_mov_b32 s6, 0x800000
	v_add3_u32 v156, v132, v134, s6
	v_lshl_add_u64 v[132:133], v[156:157], 1, s[88:89]
	global_store_dwordx4 v[132:133], v[128:131], off
	v_add_u32_e32 v132, v173, v187
	v_and_b32_e32 v133, 0xf8, v176
	v_lshl_or_b32 v132, v132, 12, v133
	s_mov_b32 s6, 0x1000000
	v_add3_u32 v156, v132, v134, s6
	v_lshl_add_u64 v[132:133], v[156:157], 1, s[88:89]
	global_store_dwordx4 v[132:133], v[128:131], off

.LBB0_349:
	s_or_b64 exec, exec, s[36:37]
	s_and_b64 vcc, exec, s[4:5]
	v_mov_b32_e32 v140, v96
	v_mov_b32_e32 v141, v97
	v_mov_b32_e32 v142, v98
	v_mov_b32_e32 v143, v99
	v_mov_b32_e32 v136, v100
	v_mov_b32_e32 v137, v101
	v_mov_b32_e32 v138, v102
	v_mov_b32_e32 v139, v103
	s_cbranch_vccnz .LBB0_351
	v_pk_mul_f32 v[196:197], v[100:101], v[132:133] op_sel:[1,0] op_sel_hi:[0,0]
	v_pk_mul_f32 v[146:147], v[100:101], v[128:129]
	v_pk_fma_f32 v[136:137], v[100:101], v[128:129], v[196:197] op_sel_hi:[1,0,1]
	v_mov_b32_e32 v132, v129
	v_mul_f32_e32 v128, v103, v133
	v_pk_fma_f32 v[138:139], v[102:103], v[132:133], v[128:129] op_sel_hi:[1,1,0] neg_lo:[0,0,1] neg_hi:[0,0,1]
	v_mov_b32_e32 v128, v133
	v_mul_f32_e32 v132, v103, v129
	v_pk_mul_f32 v[198:199], v[96:97], v[134:135] op_sel:[1,0] op_sel_hi:[0,0]
	v_pk_fma_f32 v[128:129], v[102:103], v[128:129], v[132:133] op_sel_hi:[1,1,0]
	v_pk_mul_f32 v[132:133], v[96:97], v[130:131]
	v_pk_fma_f32 v[140:141], v[96:97], v[130:131], v[198:199] op_sel_hi:[1,0,1]
	v_mov_b32_e32 v134, v131
	v_mul_f32_e32 v130, v99, v135
	v_pk_fma_f32 v[142:143], v[98:99], v[134:135], v[130:131] op_sel_hi:[1,1,0] neg_lo:[0,0,1] neg_hi:[0,0,1]
	v_mov_b32_e32 v130, v135
	v_mul_f32_e32 v134, v99, v131
	v_pk_fma_f32 v[130:131], v[98:99], v[130:131], v[134:135] op_sel_hi:[1,1,0]
	v_sub_f32_e32 v140, v132, v198
	v_sub_f32_e32 v136, v146, v196
	v_mov_b32_e32 v143, v130
	v_mov_b32_e32 v139, v128
.LBB0_351:
	v_cvt_pk_bf16_f32 v128, v136, v137
	v_cvt_pk_bf16_f32 v129, v138, v139
	v_cvt_pk_bf16_f32 v130, v140, v141
	v_cvt_pk_bf16_f32 v131, v142, v143
	global_store_dwordx4 v[174:175], v[128:131], off offset:256
	s_and_saveexec_b64 s[36:37], s[8:9]
	s_cbranch_execz .LBB0_353
	s_lshl_b32 s8, s82, 21
	s_add_i32 s8, s8, 0xfc900000
	v_add_u32_e32 v134, s8, v186
	s_movk_i32 s8, 0xf000
	v_and_or_b32 v132, v193, s8, v194
	v_add_u32_e32 v156, v132, v134
	v_lshl_add_u64 v[132:133], v[156:157], 1, s[88:89]
	global_store_dwordx4 v[132:133], v[128:131], off
	v_add_u32_e32 v132, v191, v188
	v_lshl_or_b32 v132, v132, 12, v192
	s_mov_b32 s8, 0x800000
	v_add3_u32 v156, v132, v134, s8
	v_lshl_add_u64 v[132:133], v[156:157], 1, s[88:89]
	global_store_dwordx4 v[132:133], v[128:131], off
	v_add_u32_e32 v132, v173, v187
	v_and_b32_e32 v133, 0xf8, v177
	v_lshl_or_b32 v132, v132, 12, v133
	s_mov_b32 s8, 0x1000000
	v_add3_u32 v156, v132, v134, s8
	v_lshl_add_u64 v[132:133], v[156:157], 1, s[88:89]
	global_store_dwordx4 v[132:133], v[128:131], off

.LBB0_370:
	s_or_b64 exec, exec, s[36:37]
	s_and_b64 vcc, exec, s[4:5]
	v_mov_b32_e32 v140, v80
	v_mov_b32_e32 v141, v81
	v_mov_b32_e32 v142, v82
	v_mov_b32_e32 v143, v83
	v_mov_b32_e32 v136, v84
	v_mov_b32_e32 v137, v85
	v_mov_b32_e32 v138, v86
	v_mov_b32_e32 v139, v87
	s_cbranch_vccnz .LBB0_372
	v_pk_mul_f32 v[194:195], v[84:85], v[132:133] op_sel:[1,0] op_sel_hi:[0,0]
	v_pk_mul_f32 v[146:147], v[84:85], v[128:129]
	v_pk_fma_f32 v[136:137], v[84:85], v[128:129], v[194:195] op_sel_hi:[1,0,1]
	v_mov_b32_e32 v132, v129
	v_mul_f32_e32 v128, v87, v133
	v_pk_fma_f32 v[138:139], v[86:87], v[132:133], v[128:129] op_sel_hi:[1,1,0] neg_lo:[0,0,1] neg_hi:[0,0,1]
	v_mov_b32_e32 v128, v133
	v_mul_f32_e32 v132, v87, v129
	v_pk_mul_f32 v[196:197], v[80:81], v[134:135] op_sel:[1,0] op_sel_hi:[0,0]
	v_pk_fma_f32 v[128:129], v[86:87], v[128:129], v[132:133] op_sel_hi:[1,1,0]
	v_pk_mul_f32 v[132:133], v[80:81], v[130:131]
	v_pk_fma_f32 v[140:141], v[80:81], v[130:131], v[196:197] op_sel_hi:[1,0,1]
	v_mov_b32_e32 v134, v131
	v_mul_f32_e32 v130, v83, v135
	v_pk_fma_f32 v[142:143], v[82:83], v[134:135], v[130:131] op_sel_hi:[1,1,0] neg_lo:[0,0,1] neg_hi:[0,0,1]
	v_mov_b32_e32 v130, v135
	v_mul_f32_e32 v134, v83, v131
	v_pk_fma_f32 v[130:131], v[82:83], v[130:131], v[134:135] op_sel_hi:[1,1,0]
	v_sub_f32_e32 v140, v132, v196
	v_sub_f32_e32 v136, v146, v194
	v_mov_b32_e32 v143, v130
	v_mov_b32_e32 v139, v128
.LBB0_372:
	v_cvt_pk_bf16_f32 v128, v136, v137
	v_cvt_pk_bf16_f32 v129, v138, v139
	v_cvt_pk_bf16_f32 v130, v140, v141
	v_cvt_pk_bf16_f32 v131, v142, v143
	global_store_dwordx4 v[174:175], v[128:131], off offset:256
	s_and_saveexec_b64 s[36:37], s[8:9]
	s_cbranch_execz .LBB0_374
	s_lshl_b32 s8, s82, 21
	s_add_i32 s8, s8, 0xfc900000
	v_lshlrev_b32_e32 v132, 3, v184
	v_add_u32_e32 v134, s8, v186
	v_and_b32_e32 v132, 0xf8, v132
	s_movk_i32 s8, 0xf000
	v_and_or_b32 v132, v193, s8, v132
	v_add_u32_e32 v156, v132, v134
	v_lshl_add_u64 v[132:133], v[156:157], 1, s[88:89]
	global_store_dwordx4 v[132:133], v[128:131], off
	v_add_u32_e32 v132, v191, v188
	v_lshl_or_b32 v132, v132, 12, v192
	s_mov_b32 s8, 0x800000
	v_add3_u32 v156, v132, v134, s8
	v_lshl_add_u64 v[132:133], v[156:157], 1, s[88:89]
	global_store_dwordx4 v[132:133], v[128:131], off
	v_add_u32_e32 v132, v173, v187
	v_and_b32_e32 v133, 0xf8, v177
	v_lshl_or_b32 v132, v132, 12, v133
	s_mov_b32 s8, 0x1000000
	v_add3_u32 v156, v132, v134, s8
	v_lshl_add_u64 v[132:133], v[156:157], 1, s[88:89]
	global_store_dwordx4 v[132:133], v[128:131], off

.LBB0_391:
	s_or_b64 exec, exec, s[36:37]
	s_and_b64 vcc, exec, s[4:5]
	v_mov_b32_e32 v140, v64
	v_mov_b32_e32 v141, v65
	v_mov_b32_e32 v142, v66
	v_mov_b32_e32 v143, v67
	v_mov_b32_e32 v136, v68
	v_mov_b32_e32 v137, v69
	v_mov_b32_e32 v138, v70
	v_mov_b32_e32 v139, v71
	s_cbranch_vccnz .LBB0_393
	v_pk_mul_f32 v[196:197], v[68:69], v[132:133] op_sel:[1,0] op_sel_hi:[0,0]
	v_pk_mul_f32 v[146:147], v[68:69], v[128:129]
	v_pk_fma_f32 v[136:137], v[68:69], v[128:129], v[196:197] op_sel_hi:[1,0,1]
	v_mov_b32_e32 v132, v129
	v_mul_f32_e32 v128, v71, v133
	v_pk_fma_f32 v[138:139], v[70:71], v[132:133], v[128:129] op_sel_hi:[1,1,0] neg_lo:[0,0,1] neg_hi:[0,0,1]
	v_mov_b32_e32 v128, v133
	v_mul_f32_e32 v132, v71, v129
	v_pk_mul_f32 v[198:199], v[64:65], v[134:135] op_sel:[1,0] op_sel_hi:[0,0]
	v_pk_fma_f32 v[128:129], v[70:71], v[128:129], v[132:133] op_sel_hi:[1,1,0]
	v_pk_mul_f32 v[132:133], v[64:65], v[130:131]
	v_pk_fma_f32 v[140:141], v[64:65], v[130:131], v[198:199] op_sel_hi:[1,0,1]
	v_mov_b32_e32 v134, v131
	v_mul_f32_e32 v130, v67, v135
	v_pk_fma_f32 v[142:143], v[66:67], v[134:135], v[130:131] op_sel_hi:[1,1,0] neg_lo:[0,0,1] neg_hi:[0,0,1]
	v_mov_b32_e32 v130, v135
	v_mul_f32_e32 v134, v67, v131
	v_pk_fma_f32 v[130:131], v[66:67], v[130:131], v[134:135] op_sel_hi:[1,1,0]
	v_sub_f32_e32 v140, v132, v198
	v_sub_f32_e32 v136, v146, v196
	v_mov_b32_e32 v143, v130
	v_mov_b32_e32 v139, v128

.LBB0_412:
	s_or_b64 exec, exec, s[36:37]
	s_and_b64 vcc, exec, s[4:5]
	v_mov_b32_e32 v140, v48
	v_mov_b32_e32 v141, v49
	v_mov_b32_e32 v142, v50
	v_mov_b32_e32 v143, v51
	v_mov_b32_e32 v136, v52
	v_mov_b32_e32 v137, v53
	v_mov_b32_e32 v138, v54
	v_mov_b32_e32 v139, v55
	s_cbranch_vccnz .LBB0_414
	v_pk_mul_f32 v[192:193], v[52:53], v[132:133] op_sel:[1,0] op_sel_hi:[0,0]
	v_pk_mul_f32 v[146:147], v[52:53], v[128:129]
	v_pk_fma_f32 v[136:137], v[52:53], v[128:129], v[192:193] op_sel_hi:[1,0,1]
	v_mov_b32_e32 v132, v129
	v_mul_f32_e32 v128, v55, v133
	v_pk_fma_f32 v[138:139], v[54:55], v[132:133], v[128:129] op_sel_hi:[1,1,0] neg_lo:[0,0,1] neg_hi:[0,0,1]
	v_mov_b32_e32 v128, v133
	v_mul_f32_e32 v132, v55, v129
	v_pk_mul_f32 v[194:195], v[48:49], v[134:135] op_sel:[1,0] op_sel_hi:[0,0]
	v_pk_fma_f32 v[128:129], v[54:55], v[128:129], v[132:133] op_sel_hi:[1,1,0]
	v_pk_mul_f32 v[132:133], v[48:49], v[130:131]
	v_pk_fma_f32 v[140:141], v[48:49], v[130:131], v[194:195] op_sel_hi:[1,0,1]
	v_mov_b32_e32 v134, v131
	v_mul_f32_e32 v130, v51, v135
	v_pk_fma_f32 v[142:143], v[50:51], v[134:135], v[130:131] op_sel_hi:[1,1,0] neg_lo:[0,0,1] neg_hi:[0,0,1]
	v_mov_b32_e32 v130, v135
	v_mul_f32_e32 v134, v51, v131
	v_pk_fma_f32 v[130:131], v[50:51], v[130:131], v[134:135] op_sel_hi:[1,1,0]
	v_sub_f32_e32 v140, v132, v194
	v_sub_f32_e32 v136, v146, v192
	v_mov_b32_e32 v143, v130
	v_mov_b32_e32 v139, v128
.LBB0_414:
	v_cvt_pk_bf16_f32 v128, v136, v137
	v_cvt_pk_bf16_f32 v129, v138, v139
	v_cvt_pk_bf16_f32 v130, v140, v141
	v_cvt_pk_bf16_f32 v131, v142, v143
	global_store_dwordx4 v[172:173], v[128:131], off offset:256
	s_and_saveexec_b64 s[36:37], s[8:9]
	s_cbranch_execz .LBB0_416
	s_lshl_b32 s8, s82, 21
	s_add_i32 s8, s8, 0xfc900000
	v_lshlrev_b32_e32 v132, 3, v184
	v_add_u32_e32 v134, s8, v186
	v_and_b32_e32 v132, 0xf8, v132
	s_movk_i32 s8, 0xf000
	v_and_or_b32 v132, v191, s8, v132
	v_add_u32_e32 v156, v132, v134
	v_lshl_add_u64 v[132:133], v[156:157], 1, s[88:89]
	global_store_dwordx4 v[132:133], v[128:131], off
	v_add_u32_e32 v132, v177, v188
	v_lshl_or_b32 v132, v132, 12, v190
	s_mov_b32 s8, 0x800000
	v_add3_u32 v156, v132, v134, s8
	v_lshl_add_u64 v[132:133], v[156:157], 1, s[88:89]
	global_store_dwordx4 v[132:133], v[128:131], off
	v_add_u32_e32 v132, v175, v187
	v_and_b32_e32 v133, 0xf8, v176
	v_lshl_or_b32 v132, v132, 12, v133
	s_mov_b32 s8, 0x1000000
	v_add3_u32 v156, v132, v134, s8
	v_lshl_add_u64 v[132:133], v[156:157], 1, s[88:89]
	global_store_dwordx4 v[132:133], v[128:131], off

.LBB0_433:
	s_or_b64 exec, exec, s[36:37]
	s_and_b64 vcc, exec, s[4:5]
	v_mov_b32_e32 v140, v32
	v_mov_b32_e32 v141, v33
	v_mov_b32_e32 v142, v34
	v_mov_b32_e32 v143, v35
	v_mov_b32_e32 v136, v36
	v_mov_b32_e32 v137, v37
	v_mov_b32_e32 v138, v38
	v_mov_b32_e32 v139, v39
	s_cbranch_vccnz .LBB0_435
	v_pk_mul_f32 v[194:195], v[36:37], v[132:133] op_sel:[1,0] op_sel_hi:[0,0]
	v_pk_mul_f32 v[146:147], v[36:37], v[128:129]
	v_pk_fma_f32 v[136:137], v[36:37], v[128:129], v[194:195] op_sel_hi:[1,0,1]
	v_mov_b32_e32 v132, v129
	v_mul_f32_e32 v128, v39, v133
	v_pk_fma_f32 v[138:139], v[38:39], v[132:133], v[128:129] op_sel_hi:[1,1,0] neg_lo:[0,0,1] neg_hi:[0,0,1]
	v_mov_b32_e32 v128, v133
	v_mul_f32_e32 v132, v39, v129
	v_pk_mul_f32 v[196:197], v[32:33], v[134:135] op_sel:[1,0] op_sel_hi:[0,0]
	v_pk_fma_f32 v[128:129], v[38:39], v[128:129], v[132:133] op_sel_hi:[1,1,0]
	v_pk_mul_f32 v[132:133], v[32:33], v[130:131]
	v_pk_fma_f32 v[140:141], v[32:33], v[130:131], v[196:197] op_sel_hi:[1,0,1]
	v_mov_b32_e32 v134, v131
	v_mul_f32_e32 v130, v35, v135
	v_pk_fma_f32 v[142:143], v[34:35], v[134:135], v[130:131] op_sel_hi:[1,1,0] neg_lo:[0,0,1] neg_hi:[0,0,1]
	v_mov_b32_e32 v130, v135
	v_mul_f32_e32 v134, v35, v131
	v_pk_fma_f32 v[130:131], v[34:35], v[130:131], v[134:135] op_sel_hi:[1,1,0]
	v_sub_f32_e32 v140, v132, v196
	v_sub_f32_e32 v136, v146, v194
	v_mov_b32_e32 v143, v130
	v_mov_b32_e32 v139, v128
.LBB0_435:
	v_cvt_pk_bf16_f32 v128, v136, v137
	v_cvt_pk_bf16_f32 v129, v138, v139
	v_cvt_pk_bf16_f32 v130, v140, v141
	v_cvt_pk_bf16_f32 v131, v142, v143
	global_store_dwordx4 v[172:173], v[128:131], off offset:256
	s_and_saveexec_b64 s[36:37], s[8:9]
	s_cbranch_execz .LBB0_437
	s_lshl_b32 s8, s82, 21
	s_add_i32 s8, s8, 0xfc900000
	v_add_u32_e32 v134, s8, v186
	s_movk_i32 s8, 0xf000
	v_and_or_b32 v132, v191, s8, v192
	v_add_u32_e32 v156, v132, v134
	v_lshl_add_u64 v[132:133], v[156:157], 1, s[88:89]
	global_store_dwordx4 v[132:133], v[128:131], off
	v_add_u32_e32 v132, v177, v188
	v_lshl_or_b32 v132, v132, 12, v190
	s_mov_b32 s8, 0x800000
	v_add3_u32 v156, v132, v134, s8
	v_lshl_add_u64 v[132:133], v[156:157], 1, s[88:89]
	global_store_dwordx4 v[132:133], v[128:131], off
	v_add_u32_e32 v132, v175, v187
	v_and_b32_e32 v133, 0xf8, v176
	v_lshl_or_b32 v132, v132, 12, v133
	s_mov_b32 s8, 0x1000000
	v_add3_u32 v156, v132, v134, s8
	v_lshl_add_u64 v[132:133], v[156:157], 1, s[88:89]
	global_store_dwordx4 v[132:133], v[128:131], off

.LBB0_454:
	s_or_b64 exec, exec, s[36:37]
	s_and_b64 vcc, exec, s[4:5]
	v_mov_b32_e32 v140, v16
	v_mov_b32_e32 v141, v17
	v_mov_b32_e32 v142, v18
	v_mov_b32_e32 v143, v19
	v_mov_b32_e32 v136, v20
	v_mov_b32_e32 v137, v21
	v_mov_b32_e32 v138, v22
	v_mov_b32_e32 v139, v23
	s_cbranch_vccnz .LBB0_456
	v_pk_mul_f32 v[192:193], v[20:21], v[132:133] op_sel:[1,0] op_sel_hi:[0,0]
	v_pk_mul_f32 v[146:147], v[20:21], v[128:129]
	v_pk_fma_f32 v[136:137], v[20:21], v[128:129], v[192:193] op_sel_hi:[1,0,1]
	v_mov_b32_e32 v132, v129
	v_mul_f32_e32 v128, v23, v133
	v_pk_fma_f32 v[138:139], v[22:23], v[132:133], v[128:129] op_sel_hi:[1,1,0] neg_lo:[0,0,1] neg_hi:[0,0,1]
	v_mov_b32_e32 v128, v133
	v_mul_f32_e32 v132, v23, v129
	v_pk_mul_f32 v[194:195], v[16:17], v[134:135] op_sel:[1,0] op_sel_hi:[0,0]
	v_pk_fma_f32 v[128:129], v[22:23], v[128:129], v[132:133] op_sel_hi:[1,1,0]
	v_pk_mul_f32 v[132:133], v[16:17], v[130:131]
	v_pk_fma_f32 v[140:141], v[16:17], v[130:131], v[194:195] op_sel_hi:[1,0,1]
	v_mov_b32_e32 v134, v131
	v_mul_f32_e32 v130, v19, v135
	v_pk_fma_f32 v[142:143], v[18:19], v[134:135], v[130:131] op_sel_hi:[1,1,0] neg_lo:[0,0,1] neg_hi:[0,0,1]
	v_mov_b32_e32 v130, v135
	v_mul_f32_e32 v134, v19, v131
	v_pk_fma_f32 v[130:131], v[18:19], v[130:131], v[134:135] op_sel_hi:[1,1,0]
	v_sub_f32_e32 v140, v132, v194
	v_sub_f32_e32 v136, v146, v192
	v_mov_b32_e32 v143, v130
	v_mov_b32_e32 v139, v128

.LBB0_475:
	s_or_b64 exec, exec, s[34:35]
	s_and_b64 vcc, exec, s[4:5]
	v_mov_b32_e32 v140, v0
	v_mov_b32_e32 v141, v1
	v_mov_b32_e32 v142, v2
	v_mov_b32_e32 v143, v3
	v_mov_b32_e32 v136, v4
	v_mov_b32_e32 v137, v5
	v_mov_b32_e32 v138, v6
	v_mov_b32_e32 v139, v7
	s_cbranch_vccnz .LBB0_477
	v_pk_mul_f32 v[192:193], v[4:5], v[132:133] op_sel:[1,0] op_sel_hi:[0,0]
	v_pk_mul_f32 v[146:147], v[4:5], v[128:129]
	v_pk_fma_f32 v[136:137], v[4:5], v[128:129], v[192:193] op_sel_hi:[1,0,1]
	v_mov_b32_e32 v132, v129
	v_mul_f32_e32 v128, v7, v133
	v_pk_fma_f32 v[138:139], v[6:7], v[132:133], v[128:129] op_sel_hi:[1,1,0] neg_lo:[0,0,1] neg_hi:[0,0,1]
	v_mov_b32_e32 v128, v133
	v_mul_f32_e32 v132, v7, v129
	v_pk_mul_f32 v[194:195], v[0:1], v[134:135] op_sel:[1,0] op_sel_hi:[0,0]
	v_pk_fma_f32 v[128:129], v[6:7], v[128:129], v[132:133] op_sel_hi:[1,1,0]
	v_pk_mul_f32 v[132:133], v[0:1], v[130:131]
	v_pk_fma_f32 v[140:141], v[0:1], v[130:131], v[194:195] op_sel_hi:[1,0,1]
	v_mov_b32_e32 v134, v131
	v_mul_f32_e32 v130, v3, v135
	v_pk_fma_f32 v[142:143], v[2:3], v[134:135], v[130:131] op_sel_hi:[1,1,0] neg_lo:[0,0,1] neg_hi:[0,0,1]
	v_mov_b32_e32 v130, v135
	v_mul_f32_e32 v134, v3, v131
	v_pk_fma_f32 v[130:131], v[2:3], v[130:131], v[134:135] op_sel_hi:[1,1,0]
	v_sub_f32_e32 v140, v132, v194
	v_sub_f32_e32 v136, v146, v192
	v_mov_b32_e32 v143, v130
	v_mov_b32_e32 v139, v128
.LBB0_477:
	v_cvt_pk_bf16_f32 v128, v136, v137
	v_cvt_pk_bf16_f32 v129, v138, v139
	v_cvt_pk_bf16_f32 v130, v140, v141
	v_cvt_pk_bf16_f32 v131, v142, v143
	global_store_dwordx4 v[172:173], v[128:131], off offset:256
	s_and_saveexec_b64 s[4:5], s[8:9]
	s_cbranch_execz .LBB0_479
	s_lshl_b32 s8, s82, 21
	s_add_i32 s8, s8, 0xfc900000
	v_add_u32_e32 v134, s8, v186
	s_movk_i32 s8, 0xf000
	v_and_or_b32 v132, v190, s8, v191
	v_add_u32_e32 v156, v132, v134
	v_lshl_add_u64 v[132:133], v[156:157], 1, s[88:89]
	global_store_dwordx4 v[132:133], v[128:131], off
	v_add_u32_e32 v132, v177, v188
	v_lshl_or_b32 v132, v132, 12, v189
	s_mov_b32 s8, 0x800000
	v_add3_u32 v156, v132, v134, s8
	v_lshl_add_u64 v[132:133], v[156:157], 1, s[88:89]
	global_store_dwordx4 v[132:133], v[128:131], off
	v_add_u32_e32 v132, v175, v187
	v_and_b32_e32 v133, 0xf8, v176
	v_lshl_or_b32 v132, v132, 12, v133
	s_mov_b32 s8, 0x1000000
	v_add3_u32 v156, v132, v134, s8
	v_lshl_add_u64 v[132:133], v[156:157], 1, s[88:89]
	global_store_dwordx4 v[132:133], v[128:131], off

.LBB0_492:
	v_pk_mul_f32 v[142:143], v[142:143], s[30:31] op_sel_hi:[1,0]
	v_pk_mul_f32 v[170:171], v[144:145], s[30:31] op_sel_hi:[1,0]
	v_cvt_pk_bf16_f32 v144, v142, v143
	v_mov_b64_e32 v[142:143], s[0:1]
	v_lshl_add_u32 v136, v185, 3, s59
	v_mad_i64_i32 v[142:143], s[6:7], v140, s28, v[142:143]
	s_lshl_b32 s20, s82, 9
	v_ashrrev_i32_e32 v137, 31, v136
	v_pk_mul_f32 v[168:169], v[168:169], s[30:31] op_sel_hi:[1,0]
	v_pk_mul_f32 v[146:147], v[146:147], s[30:31] op_sel_hi:[1,0]
	v_lshl_add_u64 v[142:143], v[142:143], 0, s[20:21]
	v_cvt_pk_bf16_f32 v145, v170, v171
	v_cvt_pk_bf16_f32 v146, v146, v147
	v_cvt_pk_bf16_f32 v147, v168, v169
	v_lshl_add_u64 v[142:143], v[136:137], 1, v[142:143]
	global_store_dwordx4 v[142:143], v[144:147], off
	s_and_b64 vcc, exec, s[4:5]
	v_mov_b32_e32 v168, v112
	v_mov_b32_e32 v144, v116
	v_mov_b32_e32 v145, v117
	v_mov_b32_e32 v146, v118
	v_mov_b32_e32 v147, v119
	v_mov_b32_e32 v169, v113
	v_mov_b32_e32 v170, v114
	v_mov_b32_e32 v171, v115
	s_cbranch_vccnz .LBB0_494
	v_pk_mul_f32 v[174:175], v[116:117], v[132:133] op_sel:[1,0] op_sel_hi:[0,0]
	v_pk_mul_f32 v[172:173], v[116:117], v[128:129]
	v_pk_fma_f32 v[144:145], v[116:117], v[128:129], v[174:175] op_sel_hi:[1,0,1]
	v_mov_b32_e32 v132, v129
	v_mul_f32_e32 v128, v119, v133
	v_pk_fma_f32 v[146:147], v[118:119], v[132:133], v[128:129] op_sel_hi:[1,1,0] neg_lo:[0,0,1] neg_hi:[0,0,1]
	v_mov_b32_e32 v128, v133
	v_mul_f32_e32 v132, v119, v129
	v_pk_mul_f32 v[176:177], v[112:113], v[134:135] op_sel:[1,0] op_sel_hi:[0,0]
	v_pk_fma_f32 v[128:129], v[118:119], v[128:129], v[132:133] op_sel_hi:[1,1,0]
	v_pk_mul_f32 v[132:133], v[112:113], v[130:131]
	v_pk_fma_f32 v[168:169], v[112:113], v[130:131], v[176:177] op_sel_hi:[1,0,1]
	v_mov_b32_e32 v134, v131
	v_mul_f32_e32 v130, v115, v135
	v_pk_fma_f32 v[170:171], v[114:115], v[134:135], v[130:131] op_sel_hi:[1,1,0] neg_lo:[0,0,1] neg_hi:[0,0,1]
	v_mov_b32_e32 v130, v135
	v_mul_f32_e32 v134, v115, v131
	v_pk_fma_f32 v[130:131], v[114:115], v[130:131], v[134:135] op_sel_hi:[1,1,0]
	v_sub_f32_e32 v144, v172, v174
	v_sub_f32_e32 v168, v132, v176
	v_mov_b32_e32 v147, v128
	v_mov_b32_e32 v171, v130
.LBB0_494:
	v_pk_mul_f32 v[130:131], v[146:147], s[30:31] op_sel_hi:[1,0]
	v_pk_mul_f32 v[128:129], v[144:145], s[30:31] op_sel_hi:[1,0]
	v_pk_mul_f32 v[132:133], v[170:171], s[30:31] op_sel_hi:[1,0]
	v_pk_mul_f32 v[134:135], v[168:169], s[30:31] op_sel_hi:[1,0]
	v_cvt_pk_bf16_f32 v128, v128, v129
	v_cvt_pk_bf16_f32 v129, v130, v131
	v_cvt_pk_bf16_f32 v130, v134, v135
	v_cvt_pk_bf16_f32 v131, v132, v133
	global_store_dwordx4 v[142:143], v[128:131], off offset:256
	v_add_u32_e32 v142, 16, v140
	s_and_b64 vcc, exec, s[4:5]
	v_ashrrev_i32_e32 v143, 31, v142
	s_cbranch_vccz .LBB0_496
	v_mov_b32_e32 v132, 0
	v_mov_b32_e32 v128, 1.0
	v_mov_b32_e32 v129, v128
	v_mov_b32_e32 v130, v128
	v_mov_b32_e32 v131, v128
	v_mov_b32_e32 v133, v132
	v_mov_b32_e32 v134, v132
	v_mov_b32_e32 v135, v132
	s_branch .LBB0_497

.LBB0_499:
	v_pk_mul_f32 v[146:147], v[146:147], s[30:31] op_sel_hi:[1,0]
	v_pk_mul_f32 v[144:145], v[144:145], s[30:31] op_sel_hi:[1,0]
	v_pk_mul_f32 v[168:169], v[168:169], s[30:31] op_sel_hi:[1,0]
	s_lshl_b32 s8, s82, 8
	v_cvt_pk_bf16_f32 v144, v144, v145
	v_cvt_pk_bf16_f32 v145, v146, v147
	v_cvt_pk_bf16_f32 v146, v168, v169
	v_mov_b64_e32 v[168:169], s[0:1]
	v_mad_i64_i32 v[142:143], s[6:7], v142, s28, v[168:169]
	s_lshl_b32 s20, s8, 1
	v_pk_mul_f32 v[170:171], v[170:171], s[30:31] op_sel_hi:[1,0]
	v_lshl_add_u64 v[142:143], v[142:143], 0, s[20:21]
	v_cvt_pk_bf16_f32 v147, v170, v171
	v_lshl_add_u64 v[142:143], v[136:137], 1, v[142:143]
	global_store_dwordx4 v[142:143], v[144:147], off
	s_and_b64 vcc, exec, s[4:5]
	v_mov_b32_e32 v168, v96
	v_mov_b32_e32 v144, v100
	v_mov_b32_e32 v145, v101
	v_mov_b32_e32 v146, v102
	v_mov_b32_e32 v147, v103
	v_mov_b32_e32 v169, v97
	v_mov_b32_e32 v170, v98
	v_mov_b32_e32 v171, v99
	s_cbranch_vccnz .LBB0_501
	v_pk_mul_f32 v[174:175], v[100:101], v[132:133] op_sel:[1,0] op_sel_hi:[0,0]
	v_pk_mul_f32 v[172:173], v[100:101], v[128:129]
	v_pk_fma_f32 v[144:145], v[100:101], v[128:129], v[174:175] op_sel_hi:[1,0,1]
	v_mov_b32_e32 v132, v129
	v_mul_f32_e32 v128, v103, v133
	v_pk_fma_f32 v[146:147], v[102:103], v[132:133], v[128:129] op_sel_hi:[1,1,0] neg_lo:[0,0,1] neg_hi:[0,0,1]
	v_mov_b32_e32 v128, v133
	v_mul_f32_e32 v132, v103, v129
	v_pk_mul_f32 v[176:177], v[96:97], v[134:135] op_sel:[1,0] op_sel_hi:[0,0]
	v_pk_fma_f32 v[128:129], v[102:103], v[128:129], v[132:133] op_sel_hi:[1,1,0]
	v_pk_mul_f32 v[132:133], v[96:97], v[130:131]
	v_pk_fma_f32 v[168:169], v[96:97], v[130:131], v[176:177] op_sel_hi:[1,0,1]
	v_mov_b32_e32 v134, v131
	v_mul_f32_e32 v130, v99, v135
	v_pk_fma_f32 v[170:171], v[98:99], v[134:135], v[130:131] op_sel_hi:[1,1,0] neg_lo:[0,0,1] neg_hi:[0,0,1]
	v_mov_b32_e32 v130, v135
	v_mul_f32_e32 v134, v99, v131
	v_pk_fma_f32 v[130:131], v[98:99], v[130:131], v[134:135] op_sel_hi:[1,1,0]
	v_sub_f32_e32 v144, v172, v174
	v_sub_f32_e32 v168, v132, v176
	v_mov_b32_e32 v147, v128
	v_mov_b32_e32 v171, v130
.LBB0_501:
	v_pk_mul_f32 v[130:131], v[146:147], s[30:31] op_sel_hi:[1,0]
	v_pk_mul_f32 v[128:129], v[144:145], s[30:31] op_sel_hi:[1,0]
	v_pk_mul_f32 v[132:133], v[170:171], s[30:31] op_sel_hi:[1,0]
	v_pk_mul_f32 v[134:135], v[168:169], s[30:31] op_sel_hi:[1,0]
	v_cvt_pk_bf16_f32 v128, v128, v129
	v_cvt_pk_bf16_f32 v129, v130, v131
	v_cvt_pk_bf16_f32 v130, v134, v135
	v_cvt_pk_bf16_f32 v131, v132, v133
	global_store_dwordx4 v[142:143], v[128:131], off offset:256
	v_add_u32_e32 v142, 32, v140
	s_and_b64 vcc, exec, s[4:5]
	v_ashrrev_i32_e32 v143, 31, v142
	s_cbranch_vccz .LBB0_503
	v_mov_b32_e32 v132, 0
	v_mov_b32_e32 v128, 1.0
	v_mov_b32_e32 v129, v128
	v_mov_b32_e32 v130, v128
	v_mov_b32_e32 v131, v128
	v_mov_b32_e32 v133, v132
	v_mov_b32_e32 v134, v132
	v_mov_b32_e32 v135, v132
	s_branch .LBB0_504

.LBB0_506:
	v_pk_mul_f32 v[146:147], v[146:147], s[30:31] op_sel_hi:[1,0]
	v_pk_mul_f32 v[144:145], v[144:145], s[30:31] op_sel_hi:[1,0]
	v_pk_mul_f32 v[168:169], v[168:169], s[30:31] op_sel_hi:[1,0]
	v_cvt_pk_bf16_f32 v144, v144, v145
	v_cvt_pk_bf16_f32 v145, v146, v147
	v_cvt_pk_bf16_f32 v146, v168, v169
	v_mov_b64_e32 v[168:169], s[0:1]
	v_mad_i64_i32 v[142:143], s[6:7], v142, s28, v[168:169]
	v_pk_mul_f32 v[170:171], v[170:171], s[30:31] op_sel_hi:[1,0]
	v_lshl_add_u64 v[142:143], v[142:143], 0, s[20:21]
	v_cvt_pk_bf16_f32 v147, v170, v171
	v_lshl_add_u64 v[142:143], v[136:137], 1, v[142:143]
	global_store_dwordx4 v[142:143], v[144:147], off
	s_and_b64 vcc, exec, s[4:5]
	v_mov_b32_e32 v168, v80
	v_mov_b32_e32 v144, v84
	v_mov_b32_e32 v145, v85
	v_mov_b32_e32 v146, v86
	v_mov_b32_e32 v147, v87
	v_mov_b32_e32 v169, v81
	v_mov_b32_e32 v170, v82
	v_mov_b32_e32 v171, v83
	s_cbranch_vccnz .LBB0_508
	v_pk_mul_f32 v[174:175], v[84:85], v[132:133] op_sel:[1,0] op_sel_hi:[0,0]
	v_pk_mul_f32 v[172:173], v[84:85], v[128:129]
	v_pk_fma_f32 v[144:145], v[84:85], v[128:129], v[174:175] op_sel_hi:[1,0,1]
	v_mov_b32_e32 v132, v129
	v_mul_f32_e32 v128, v87, v133
	v_pk_fma_f32 v[146:147], v[86:87], v[132:133], v[128:129] op_sel_hi:[1,1,0] neg_lo:[0,0,1] neg_hi:[0,0,1]
	v_mov_b32_e32 v128, v133
	v_mul_f32_e32 v132, v87, v129
	v_pk_mul_f32 v[176:177], v[80:81], v[134:135] op_sel:[1,0] op_sel_hi:[0,0]
	v_pk_fma_f32 v[128:129], v[86:87], v[128:129], v[132:133] op_sel_hi:[1,1,0]
	v_pk_mul_f32 v[132:133], v[80:81], v[130:131]
	v_pk_fma_f32 v[168:169], v[80:81], v[130:131], v[176:177] op_sel_hi:[1,0,1]
	v_mov_b32_e32 v134, v131
	v_mul_f32_e32 v130, v83, v135
	v_pk_fma_f32 v[170:171], v[82:83], v[134:135], v[130:131] op_sel_hi:[1,1,0] neg_lo:[0,0,1] neg_hi:[0,0,1]
	v_mov_b32_e32 v130, v135
	v_mul_f32_e32 v134, v83, v131
	v_pk_fma_f32 v[130:131], v[82:83], v[130:131], v[134:135] op_sel_hi:[1,1,0]
	v_sub_f32_e32 v144, v172, v174
	v_sub_f32_e32 v168, v132, v176
	v_mov_b32_e32 v147, v128
	v_mov_b32_e32 v171, v130
.LBB0_508:
	v_pk_mul_f32 v[130:131], v[146:147], s[30:31] op_sel_hi:[1,0]
	v_pk_mul_f32 v[128:129], v[144:145], s[30:31] op_sel_hi:[1,0]
	v_pk_mul_f32 v[132:133], v[170:171], s[30:31] op_sel_hi:[1,0]
	v_pk_mul_f32 v[134:135], v[168:169], s[30:31] op_sel_hi:[1,0]
	v_cvt_pk_bf16_f32 v128, v128, v129
	v_cvt_pk_bf16_f32 v129, v130, v131
	v_cvt_pk_bf16_f32 v130, v134, v135
	v_cvt_pk_bf16_f32 v131, v132, v133
	global_store_dwordx4 v[142:143], v[128:131], off offset:256
	v_add_u32_e32 v142, 48, v140
	s_and_b64 vcc, exec, s[4:5]
	v_ashrrev_i32_e32 v143, 31, v142
	s_cbranch_vccz .LBB0_510
	v_mov_b32_e32 v132, 0
	v_mov_b32_e32 v128, 1.0
	v_mov_b32_e32 v129, v128
	v_mov_b32_e32 v130, v128
	v_mov_b32_e32 v131, v128
	v_mov_b32_e32 v133, v132
	v_mov_b32_e32 v134, v132
	v_mov_b32_e32 v135, v132
	s_branch .LBB0_511

.LBB0_513:
	v_pk_mul_f32 v[146:147], v[146:147], s[30:31] op_sel_hi:[1,0]
	v_pk_mul_f32 v[144:145], v[144:145], s[30:31] op_sel_hi:[1,0]
	v_pk_mul_f32 v[168:169], v[168:169], s[30:31] op_sel_hi:[1,0]
	v_cvt_pk_bf16_f32 v144, v144, v145
	v_cvt_pk_bf16_f32 v145, v146, v147
	v_cvt_pk_bf16_f32 v146, v168, v169
	v_mov_b64_e32 v[168:169], s[0:1]
	v_mad_i64_i32 v[142:143], s[6:7], v142, s28, v[168:169]
	v_pk_mul_f32 v[170:171], v[170:171], s[30:31] op_sel_hi:[1,0]
	v_lshl_add_u64 v[142:143], v[142:143], 0, s[20:21]
	v_cvt_pk_bf16_f32 v147, v170, v171
	v_lshl_add_u64 v[142:143], v[136:137], 1, v[142:143]
	global_store_dwordx4 v[142:143], v[144:147], off
	s_and_b64 vcc, exec, s[4:5]
	v_mov_b32_e32 v168, v64
	v_mov_b32_e32 v144, v68
	v_mov_b32_e32 v145, v69
	v_mov_b32_e32 v146, v70
	v_mov_b32_e32 v147, v71
	v_mov_b32_e32 v169, v65
	v_mov_b32_e32 v170, v66
	v_mov_b32_e32 v171, v67
	s_cbranch_vccnz .LBB0_515
	v_pk_mul_f32 v[174:175], v[68:69], v[132:133] op_sel:[1,0] op_sel_hi:[0,0]
	v_pk_mul_f32 v[172:173], v[68:69], v[128:129]
	v_pk_fma_f32 v[144:145], v[68:69], v[128:129], v[174:175] op_sel_hi:[1,0,1]
	v_mov_b32_e32 v132, v129
	v_mul_f32_e32 v128, v71, v133
	v_pk_fma_f32 v[146:147], v[70:71], v[132:133], v[128:129] op_sel_hi:[1,1,0] neg_lo:[0,0,1] neg_hi:[0,0,1]
	v_mov_b32_e32 v128, v133
	v_mul_f32_e32 v132, v71, v129
	v_pk_mul_f32 v[176:177], v[64:65], v[134:135] op_sel:[1,0] op_sel_hi:[0,0]
	v_pk_fma_f32 v[128:129], v[70:71], v[128:129], v[132:133] op_sel_hi:[1,1,0]
	v_pk_mul_f32 v[132:133], v[64:65], v[130:131]
	v_pk_fma_f32 v[168:169], v[64:65], v[130:131], v[176:177] op_sel_hi:[1,0,1]
	v_mov_b32_e32 v134, v131
	v_mul_f32_e32 v130, v67, v135
	v_pk_fma_f32 v[170:171], v[66:67], v[134:135], v[130:131] op_sel_hi:[1,1,0] neg_lo:[0,0,1] neg_hi:[0,0,1]
	v_mov_b32_e32 v130, v135
	v_mul_f32_e32 v134, v67, v131
	v_pk_fma_f32 v[130:131], v[66:67], v[130:131], v[134:135] op_sel_hi:[1,1,0]
	v_sub_f32_e32 v144, v172, v174
	v_sub_f32_e32 v168, v132, v176
	v_mov_b32_e32 v147, v128
	v_mov_b32_e32 v171, v130
.LBB0_515:
	v_pk_mul_f32 v[130:131], v[146:147], s[30:31] op_sel_hi:[1,0]
	v_pk_mul_f32 v[128:129], v[144:145], s[30:31] op_sel_hi:[1,0]
	v_pk_mul_f32 v[132:133], v[170:171], s[30:31] op_sel_hi:[1,0]
	v_pk_mul_f32 v[134:135], v[168:169], s[30:31] op_sel_hi:[1,0]
	v_cvt_pk_bf16_f32 v128, v128, v129
	v_cvt_pk_bf16_f32 v129, v130, v131
	v_cvt_pk_bf16_f32 v130, v134, v135
	v_cvt_pk_bf16_f32 v131, v132, v133
	global_store_dwordx4 v[142:143], v[128:131], off offset:256
	v_add_u32_e32 v142, 0x80, v140
	s_and_b64 vcc, exec, s[4:5]
	v_ashrrev_i32_e32 v143, 31, v142
	s_cbranch_vccz .LBB0_517
	v_mov_b32_e32 v132, 0
	v_mov_b32_e32 v128, 1.0
	v_mov_b32_e32 v129, v128
	v_mov_b32_e32 v130, v128
	v_mov_b32_e32 v131, v128
	v_mov_b32_e32 v133, v132
	v_mov_b32_e32 v134, v132
	v_mov_b32_e32 v135, v132
	s_branch .LBB0_518

.LBB0_520:
	v_pk_mul_f32 v[146:147], v[146:147], s[30:31] op_sel_hi:[1,0]
	v_pk_mul_f32 v[144:145], v[144:145], s[30:31] op_sel_hi:[1,0]
	v_pk_mul_f32 v[168:169], v[168:169], s[30:31] op_sel_hi:[1,0]
	v_cvt_pk_bf16_f32 v144, v144, v145
	v_cvt_pk_bf16_f32 v145, v146, v147
	v_cvt_pk_bf16_f32 v146, v168, v169
	v_mov_b64_e32 v[168:169], s[0:1]
	v_mad_i64_i32 v[142:143], s[6:7], v142, s28, v[168:169]
	v_pk_mul_f32 v[170:171], v[170:171], s[30:31] op_sel_hi:[1,0]
	v_lshl_add_u64 v[142:143], v[142:143], 0, s[20:21]
	v_cvt_pk_bf16_f32 v147, v170, v171
	v_lshl_add_u64 v[142:143], v[136:137], 1, v[142:143]
	global_store_dwordx4 v[142:143], v[144:147], off
	s_and_b64 vcc, exec, s[4:5]
	v_mov_b32_e32 v168, v48
	v_mov_b32_e32 v144, v52
	v_mov_b32_e32 v145, v53
	v_mov_b32_e32 v146, v54
	v_mov_b32_e32 v147, v55
	v_mov_b32_e32 v169, v49
	v_mov_b32_e32 v170, v50
	v_mov_b32_e32 v171, v51
	s_cbranch_vccnz .LBB0_522
	v_pk_mul_f32 v[174:175], v[52:53], v[132:133] op_sel:[1,0] op_sel_hi:[0,0]
	v_pk_mul_f32 v[172:173], v[52:53], v[128:129]
	v_pk_fma_f32 v[144:145], v[52:53], v[128:129], v[174:175] op_sel_hi:[1,0,1]
	v_mov_b32_e32 v132, v129
	v_mul_f32_e32 v128, v55, v133
	v_pk_fma_f32 v[146:147], v[54:55], v[132:133], v[128:129] op_sel_hi:[1,1,0] neg_lo:[0,0,1] neg_hi:[0,0,1]
	v_mov_b32_e32 v128, v133
	v_mul_f32_e32 v132, v55, v129
	v_pk_mul_f32 v[176:177], v[48:49], v[134:135] op_sel:[1,0] op_sel_hi:[0,0]
	v_pk_fma_f32 v[128:129], v[54:55], v[128:129], v[132:133] op_sel_hi:[1,1,0]
	v_pk_mul_f32 v[132:133], v[48:49], v[130:131]
	v_pk_fma_f32 v[168:169], v[48:49], v[130:131], v[176:177] op_sel_hi:[1,0,1]
	v_mov_b32_e32 v134, v131
	v_mul_f32_e32 v130, v51, v135
	v_pk_fma_f32 v[170:171], v[50:51], v[134:135], v[130:131] op_sel_hi:[1,1,0] neg_lo:[0,0,1] neg_hi:[0,0,1]
	v_mov_b32_e32 v130, v135
	v_mul_f32_e32 v134, v51, v131
	v_pk_fma_f32 v[130:131], v[50:51], v[130:131], v[134:135] op_sel_hi:[1,1,0]
	v_sub_f32_e32 v144, v172, v174
	v_sub_f32_e32 v168, v132, v176
	v_mov_b32_e32 v147, v128
	v_mov_b32_e32 v171, v130
.LBB0_522:
	v_pk_mul_f32 v[130:131], v[146:147], s[30:31] op_sel_hi:[1,0]
	v_pk_mul_f32 v[128:129], v[144:145], s[30:31] op_sel_hi:[1,0]
	v_pk_mul_f32 v[132:133], v[170:171], s[30:31] op_sel_hi:[1,0]
	v_pk_mul_f32 v[134:135], v[168:169], s[30:31] op_sel_hi:[1,0]
	v_cvt_pk_bf16_f32 v128, v128, v129
	v_cvt_pk_bf16_f32 v129, v130, v131
	v_cvt_pk_bf16_f32 v130, v134, v135
	v_cvt_pk_bf16_f32 v131, v132, v133
	global_store_dwordx4 v[142:143], v[128:131], off offset:256
	v_add_u32_e32 v142, 0x90, v140
	s_and_b64 vcc, exec, s[4:5]
	v_ashrrev_i32_e32 v143, 31, v142
	s_cbranch_vccz .LBB0_524
	v_mov_b32_e32 v132, 0
	v_mov_b32_e32 v128, 1.0
	v_mov_b32_e32 v129, v128
	v_mov_b32_e32 v130, v128
	v_mov_b32_e32 v131, v128
	v_mov_b32_e32 v133, v132
	v_mov_b32_e32 v134, v132
	v_mov_b32_e32 v135, v132
	s_branch .LBB0_525

.LBB0_527:
	v_pk_mul_f32 v[146:147], v[146:147], s[30:31] op_sel_hi:[1,0]
	v_pk_mul_f32 v[144:145], v[144:145], s[30:31] op_sel_hi:[1,0]
	v_pk_mul_f32 v[168:169], v[168:169], s[30:31] op_sel_hi:[1,0]
	v_cvt_pk_bf16_f32 v144, v144, v145
	v_cvt_pk_bf16_f32 v145, v146, v147
	v_cvt_pk_bf16_f32 v146, v168, v169
	v_mov_b64_e32 v[168:169], s[0:1]
	v_mad_i64_i32 v[142:143], s[6:7], v142, s28, v[168:169]
	v_pk_mul_f32 v[170:171], v[170:171], s[30:31] op_sel_hi:[1,0]
	v_lshl_add_u64 v[142:143], v[142:143], 0, s[20:21]
	v_cvt_pk_bf16_f32 v147, v170, v171
	v_lshl_add_u64 v[142:143], v[136:137], 1, v[142:143]
	global_store_dwordx4 v[142:143], v[144:147], off
	s_and_b64 vcc, exec, s[4:5]
	v_mov_b32_e32 v168, v32
	v_mov_b32_e32 v144, v36
	v_mov_b32_e32 v145, v37
	v_mov_b32_e32 v146, v38
	v_mov_b32_e32 v147, v39
	v_mov_b32_e32 v169, v33
	v_mov_b32_e32 v170, v34
	v_mov_b32_e32 v171, v35
	s_cbranch_vccnz .LBB0_529
	v_pk_mul_f32 v[174:175], v[36:37], v[132:133] op_sel:[1,0] op_sel_hi:[0,0]
	v_pk_mul_f32 v[172:173], v[36:37], v[128:129]
	v_pk_fma_f32 v[144:145], v[36:37], v[128:129], v[174:175] op_sel_hi:[1,0,1]
	v_mov_b32_e32 v132, v129
	v_mul_f32_e32 v128, v39, v133
	v_pk_fma_f32 v[146:147], v[38:39], v[132:133], v[128:129] op_sel_hi:[1,1,0] neg_lo:[0,0,1] neg_hi:[0,0,1]
	v_mov_b32_e32 v128, v133
	v_mul_f32_e32 v132, v39, v129
	v_pk_mul_f32 v[176:177], v[32:33], v[134:135] op_sel:[1,0] op_sel_hi:[0,0]
	v_pk_fma_f32 v[128:129], v[38:39], v[128:129], v[132:133] op_sel_hi:[1,1,0]
	v_pk_mul_f32 v[132:133], v[32:33], v[130:131]
	v_pk_fma_f32 v[168:169], v[32:33], v[130:131], v[176:177] op_sel_hi:[1,0,1]
	v_mov_b32_e32 v134, v131
	v_mul_f32_e32 v130, v35, v135
	v_pk_fma_f32 v[170:171], v[34:35], v[134:135], v[130:131] op_sel_hi:[1,1,0] neg_lo:[0,0,1] neg_hi:[0,0,1]
	v_mov_b32_e32 v130, v135
	v_mul_f32_e32 v134, v35, v131
	v_pk_fma_f32 v[130:131], v[34:35], v[130:131], v[134:135] op_sel_hi:[1,1,0]
	v_sub_f32_e32 v144, v172, v174
	v_sub_f32_e32 v168, v132, v176
	v_mov_b32_e32 v147, v128
	v_mov_b32_e32 v171, v130
.LBB0_529:
	v_pk_mul_f32 v[130:131], v[146:147], s[30:31] op_sel_hi:[1,0]
	v_pk_mul_f32 v[128:129], v[144:145], s[30:31] op_sel_hi:[1,0]
	v_pk_mul_f32 v[132:133], v[170:171], s[30:31] op_sel_hi:[1,0]
	v_pk_mul_f32 v[134:135], v[168:169], s[30:31] op_sel_hi:[1,0]
	v_cvt_pk_bf16_f32 v128, v128, v129
	v_cvt_pk_bf16_f32 v129, v130, v131
	v_cvt_pk_bf16_f32 v130, v134, v135
	v_cvt_pk_bf16_f32 v131, v132, v133
	global_store_dwordx4 v[142:143], v[128:131], off offset:256
	v_add_u32_e32 v142, 0xa0, v140
	s_and_b64 vcc, exec, s[4:5]
	v_ashrrev_i32_e32 v143, 31, v142
	s_cbranch_vccz .LBB0_531
	v_mov_b32_e32 v132, 0
	v_mov_b32_e32 v128, 1.0
	v_mov_b32_e32 v129, v128
	v_mov_b32_e32 v130, v128
	v_mov_b32_e32 v131, v128
	v_mov_b32_e32 v133, v132
	v_mov_b32_e32 v134, v132
	v_mov_b32_e32 v135, v132
	s_branch .LBB0_532

.LBB0_534:
	v_pk_mul_f32 v[146:147], v[146:147], s[30:31] op_sel_hi:[1,0]
	v_pk_mul_f32 v[144:145], v[144:145], s[30:31] op_sel_hi:[1,0]
	v_pk_mul_f32 v[168:169], v[168:169], s[30:31] op_sel_hi:[1,0]
	v_cvt_pk_bf16_f32 v144, v144, v145
	v_cvt_pk_bf16_f32 v145, v146, v147
	v_cvt_pk_bf16_f32 v146, v168, v169
	v_mov_b64_e32 v[168:169], s[0:1]
	v_mad_i64_i32 v[142:143], s[6:7], v142, s28, v[168:169]
	v_pk_mul_f32 v[170:171], v[170:171], s[30:31] op_sel_hi:[1,0]
	v_lshl_add_u64 v[142:143], v[142:143], 0, s[20:21]
	v_cvt_pk_bf16_f32 v147, v170, v171
	v_lshl_add_u64 v[142:143], v[136:137], 1, v[142:143]
	global_store_dwordx4 v[142:143], v[144:147], off
	s_and_b64 vcc, exec, s[4:5]
	v_mov_b32_e32 v168, v16
	v_mov_b32_e32 v144, v20
	v_mov_b32_e32 v145, v21
	v_mov_b32_e32 v146, v22
	v_mov_b32_e32 v147, v23
	v_mov_b32_e32 v169, v17
	v_mov_b32_e32 v170, v18
	v_mov_b32_e32 v171, v19
	s_cbranch_vccnz .LBB0_536
	v_pk_mul_f32 v[174:175], v[20:21], v[132:133] op_sel:[1,0] op_sel_hi:[0,0]
	v_pk_mul_f32 v[172:173], v[20:21], v[128:129]
	v_pk_fma_f32 v[144:145], v[20:21], v[128:129], v[174:175] op_sel_hi:[1,0,1]
	v_mov_b32_e32 v132, v129
	v_mul_f32_e32 v128, v23, v133
	v_pk_fma_f32 v[146:147], v[22:23], v[132:133], v[128:129] op_sel_hi:[1,1,0] neg_lo:[0,0,1] neg_hi:[0,0,1]
	v_mov_b32_e32 v128, v133
	v_mul_f32_e32 v132, v23, v129
	v_pk_mul_f32 v[176:177], v[16:17], v[134:135] op_sel:[1,0] op_sel_hi:[0,0]
	v_pk_fma_f32 v[128:129], v[22:23], v[128:129], v[132:133] op_sel_hi:[1,1,0]
	v_pk_mul_f32 v[132:133], v[16:17], v[130:131]
	v_pk_fma_f32 v[168:169], v[16:17], v[130:131], v[176:177] op_sel_hi:[1,0,1]
	v_mov_b32_e32 v134, v131
	v_mul_f32_e32 v130, v19, v135
	v_pk_fma_f32 v[170:171], v[18:19], v[134:135], v[130:131] op_sel_hi:[1,1,0] neg_lo:[0,0,1] neg_hi:[0,0,1]
	v_mov_b32_e32 v130, v135
	v_mul_f32_e32 v134, v19, v131
	v_pk_fma_f32 v[130:131], v[18:19], v[130:131], v[134:135] op_sel_hi:[1,1,0]
	v_sub_f32_e32 v144, v172, v174
	v_sub_f32_e32 v168, v132, v176
	v_mov_b32_e32 v147, v128
	v_mov_b32_e32 v171, v130
.LBB0_536:
	v_pk_mul_f32 v[130:131], v[146:147], s[30:31] op_sel_hi:[1,0]
	v_pk_mul_f32 v[128:129], v[144:145], s[30:31] op_sel_hi:[1,0]
	v_pk_mul_f32 v[132:133], v[170:171], s[30:31] op_sel_hi:[1,0]
	v_pk_mul_f32 v[134:135], v[168:169], s[30:31] op_sel_hi:[1,0]
	v_add_u32_e32 v140, 0xb0, v140
	v_cvt_pk_bf16_f32 v128, v128, v129
	v_cvt_pk_bf16_f32 v129, v130, v131
	v_cvt_pk_bf16_f32 v130, v134, v135
	v_cvt_pk_bf16_f32 v131, v132, v133
	s_and_b64 vcc, exec, s[4:5]
	v_ashrrev_i32_e32 v141, 31, v140
	global_store_dwordx4 v[142:143], v[128:131], off offset:256
	s_cbranch_vccz .LBB0_538
	v_mov_b32_e32 v132, 0
	v_mov_b32_e32 v128, 1.0
	v_mov_b32_e32 v129, v128
	v_mov_b32_e32 v130, v128
	v_mov_b32_e32 v131, v128
	v_mov_b32_e32 v133, v132
	v_mov_b32_e32 v134, v132
	v_mov_b32_e32 v135, v132
	s_branch .LBB0_539

.LBB0_541:
	v_pk_mul_f32 v[138:139], v[138:139], s[30:31] op_sel_hi:[1,0]
	v_pk_mul_f32 v[168:169], v[142:143], s[30:31] op_sel_hi:[1,0]
	v_cvt_pk_bf16_f32 v142, v138, v139
	v_mov_b64_e32 v[138:139], s[0:1]
	v_mad_i64_i32 v[138:139], s[6:7], v140, s28, v[138:139]
	v_pk_mul_f32 v[146:147], v[146:147], s[30:31] op_sel_hi:[1,0]
	v_pk_mul_f32 v[144:145], v[144:145], s[30:31] op_sel_hi:[1,0]
	v_lshl_add_u64 v[138:139], v[138:139], 0, s[20:21]
	v_cvt_pk_bf16_f32 v143, v168, v169
	v_cvt_pk_bf16_f32 v144, v144, v145
	v_cvt_pk_bf16_f32 v145, v146, v147
	v_lshl_add_u64 v[136:137], v[136:137], 1, v[138:139]
	global_store_dwordx4 v[136:137], v[142:145], off
	s_and_b64 vcc, exec, s[4:5]
	v_mov_b32_e32 v138, v4
	v_mov_b32_e32 v139, v5
	v_mov_b32_e32 v140, v6
	v_mov_b32_e32 v141, v7
	v_mov_b32_e32 v142, v0
	v_mov_b32_e32 v143, v1
	v_mov_b32_e32 v144, v2
	v_mov_b32_e32 v145, v3
	s_cbranch_vccnz .LBB0_543
	v_pk_mul_f32 v[168:169], v[4:5], v[132:133] op_sel:[1,0] op_sel_hi:[0,0]
	v_pk_mul_f32 v[146:147], v[4:5], v[128:129]
	v_pk_fma_f32 v[138:139], v[4:5], v[128:129], v[168:169] op_sel_hi:[1,0,1]
	v_mov_b32_e32 v132, v129
	v_mul_f32_e32 v128, v7, v133
	v_pk_fma_f32 v[140:141], v[6:7], v[132:133], v[128:129] op_sel_hi:[1,1,0] neg_lo:[0,0,1] neg_hi:[0,0,1]
	v_mov_b32_e32 v128, v133
	v_mul_f32_e32 v132, v7, v129
	v_pk_mul_f32 v[170:171], v[0:1], v[134:135] op_sel:[1,0] op_sel_hi:[0,0]
	v_pk_fma_f32 v[128:129], v[6:7], v[128:129], v[132:133] op_sel_hi:[1,1,0]
	v_pk_mul_f32 v[132:133], v[0:1], v[130:131]
	v_pk_fma_f32 v[142:143], v[0:1], v[130:131], v[170:171] op_sel_hi:[1,0,1]
	v_mov_b32_e32 v134, v131
	v_mul_f32_e32 v130, v3, v135
	v_pk_fma_f32 v[144:145], v[2:3], v[134:135], v[130:131] op_sel_hi:[1,1,0] neg_lo:[0,0,1] neg_hi:[0,0,1]
	v_mov_b32_e32 v130, v135
	v_mul_f32_e32 v134, v3, v131
	v_pk_fma_f32 v[130:131], v[2:3], v[130:131], v[134:135] op_sel_hi:[1,1,0]
	v_sub_f32_e32 v138, v146, v168
	v_sub_f32_e32 v142, v132, v170
	v_mov_b32_e32 v141, v128
	v_mov_b32_e32 v145, v130
.LBB0_543:
	v_pk_mul_f32 v[130:131], v[140:141], s[30:31] op_sel_hi:[1,0]
	v_pk_mul_f32 v[128:129], v[138:139], s[30:31] op_sel_hi:[1,0]
	v_pk_mul_f32 v[132:133], v[144:145], s[30:31] op_sel_hi:[1,0]
	v_pk_mul_f32 v[134:135], v[142:143], s[30:31] op_sel_hi:[1,0]
	v_cvt_pk_bf16_f32 v128, v128, v129
	v_cvt_pk_bf16_f32 v129, v130, v131
	v_cvt_pk_bf16_f32 v130, v134, v135
	v_cvt_pk_bf16_f32 v131, v132, v133
	global_store_dwordx4 v[136:137], v[128:131], off offset:256
